# sample RWKV chain: per-chunk operand prefetch addresses formed from per-chain precomputed lane parts + one scalar token offset (5 VALU adds instead of ~40 VALU per chunk)
# speedup vs baseline: 1.0021x; 1.0021x over previous
.LBB0_1250:
	s_or_b64 exec, exec, s[0:1]
	v_readlane_b32 s0, v206, 44
	v_readlane_b32 s1, v206, 45
	s_mov_b32 s2, s0
	v_writelane_b32 v206, s0, 44
	s_mov_b32 s3, s83
	v_lshlrev_b32_e32 v5, 4, v4
	v_writelane_b32 v206, s1, 45
	v_lshl_add_u64 v[2:3], v[2:3], 0, s[2:3]
	v_and_b32_e32 v106, 0xf0, v5
	v_bfe_u32 v51, v4, 3, 1
	v_readlane_b32 s0, v206, 14
	v_lshlrev_b32_e32 v4, 3, v4
	v_lshl_add_u64 v[92:93], v[2:3], 0, v[106:107]
	v_lshlrev_b32_e32 v2, 10, v51
	v_mov_b32_e32 v3, v107
	v_readlane_b32 s1, v206, 15
	v_and_b32_e32 v72, 56, v4
	v_lshlrev_b32_e32 v4, 1, v72
	v_lshl_add_u64 v[2:3], s[0:1], 0, v[2:3]
	v_mov_b32_e32 v5, v107
	v_lshl_add_u64 v[94:95], v[2:3], 0, v[4:5]
	v_ashrrev_i32_e32 v47, 31, v46
	s_setprio 2
	v_xad_u32 v2, v1, -1, s18
	s_waitcnt vmcnt(2)
	v_sub_u32_e32 v32, s18, v1
	v_cndmask_b32_e64 v2, v2, v1, s[16:17]
	v_readlane_b32 s2, v206, 6
	v_add_u32_e32 v4, 4, v1
	v_add_u32_e32 v5, -5, v32
	v_add_u32_e32 v2, s2, v2
	v_cndmask_b32_e64 v4, v5, v4, s[16:17]
	v_ashrrev_i32_e32 v3, 31, v2
	v_add_u32_e32 v4, s2, v4
	v_lshlrev_b64 v[2:3], 10, v[2:3]
	v_ashrrev_i32_e32 v5, 31, v4
	v_lshl_add_u64 v[2:3], v[92:93], 0, v[2:3]
	v_lshlrev_b64 v[4:5], 10, v[4:5]
	v_lshl_add_u64 v[4:5], v[92:93], 0, v[4:5]
	global_load_dwordx4 v[52:55], v[2:3], off
	global_load_dwordx4 v[56:59], v[4:5], off
	v_add_u32_e32 v2, 8, v1
	v_add_u32_e32 v3, -9, v32
	v_cndmask_b32_e64 v2, v3, v2, s[16:17]
	v_add_u32_e32 v4, 12, v1
	v_add_u32_e32 v5, -13, v32
	v_add_u32_e32 v2, s2, v2
	v_cndmask_b32_e64 v4, v5, v4, s[16:17]
	v_ashrrev_i32_e32 v3, 31, v2
	v_add_u32_e32 v4, s2, v4
	v_lshlrev_b64 v[2:3], 10, v[2:3]
	v_ashrrev_i32_e32 v5, 31, v4
	v_lshl_add_u64 v[2:3], v[92:93], 0, v[2:3]
	v_lshlrev_b64 v[4:5], 10, v[4:5]
	v_lshl_add_u64 v[4:5], v[92:93], 0, v[4:5]
	global_load_dwordx4 v[60:63], v[2:3], off
	global_load_dwordx4 v[64:67], v[4:5], off
	v_xad_u32 v2, v91, -1, s18
	v_cndmask_b32_e64 v2, v2, v91, s[16:17]
	v_add_u32_e32 v2, s2, v2
	v_mad_i64_i32 v[2:3], s[0:1], v2, s37, v[94:95]
	global_load_dwordx4 v[68:71], v[2:3], off
	v_add_u32_e32 v2, 16, v1
	v_subrev_u32_e32 v3, 17, v32
	v_add_u32_e32 v4, 20, v1
	v_subrev_u32_e32 v5, 21, v32
	v_add_u32_e32 v10, 24, v1
	v_subrev_u32_e32 v11, 25, v32
	v_add_u32_e32 v12, 28, v1
	v_subrev_u32_e32 v13, 29, v32
	v_cndmask_b32_e64 v2, v3, v2, s[16:17]
	v_cndmask_b32_e64 v4, v5, v4, s[16:17]
	v_cndmask_b32_e64 v10, v11, v10, s[16:17]
	v_cndmask_b32_e64 v12, v13, v12, s[16:17]
	s_waitcnt vmcnt(5)
	v_sub_u32_e32 v38, s18, v91
	v_add_u32_e32 v2, s2, v2
	v_add_u32_e32 v4, s2, v4
	v_add_u32_e32 v10, s2, v10
	v_add_u32_e32 v12, s2, v12
	v_subrev_u32_e32 v18, 17, v38
	v_add_u32_e32 v19, 16, v91
	v_ashrrev_i32_e32 v3, 31, v2
	v_ashrrev_i32_e32 v5, 31, v4
	v_ashrrev_i32_e32 v11, 31, v10
	v_ashrrev_i32_e32 v13, 31, v12
	v_cndmask_b32_e64 v18, v18, v19, s[16:17]
	v_lshlrev_b64 v[2:3], 10, v[2:3]
	v_lshlrev_b64 v[4:5], 10, v[4:5]
	v_lshlrev_b64 v[10:11], 10, v[10:11]
	v_lshlrev_b64 v[12:13], 10, v[12:13]
	v_add_u32_e32 v18, s2, v18
	v_lshl_add_u64 v[2:3], v[92:93], 0, v[2:3]
	v_lshl_add_u64 v[6:7], v[92:93], 0, v[4:5]
	v_lshl_add_u64 v[10:11], v[92:93], 0, v[10:11]
	v_lshl_add_u64 v[14:15], v[92:93], 0, v[12:13]
	v_mad_i64_i32 v[18:19], s[0:1], v18, s37, v[94:95]
	global_load_dwordx4 v[2:5], v[2:3], off
	s_nop 0
	global_load_dwordx4 v[6:9], v[6:7], off
	s_nop 0
	global_load_dwordx4 v[10:13], v[10:11], off
	s_nop 0
	global_load_dwordx4 v[14:17], v[14:15], off
	v_add_u32_e32 v20, 36, v1
	global_load_dwordx4 v[26:29], v[18:19], off
	v_add_u32_e32 v18, 32, v1
	v_subrev_u32_e32 v19, 33, v32
	v_subrev_u32_e32 v21, 37, v32
	v_add_u32_e32 v30, 40, v1
	v_subrev_u32_e32 v31, 41, v32
	v_add_u32_e32 v33, 44, v1
	v_subrev_u32_e32 v32, 45, v32
	v_cndmask_b32_e64 v18, v19, v18, s[16:17]
	v_cndmask_b32_e64 v20, v21, v20, s[16:17]
	v_cndmask_b32_e64 v30, v31, v30, s[16:17]
	v_cndmask_b32_e64 v32, v32, v33, s[16:17]
	v_add_u32_e32 v18, s2, v18
	v_add_u32_e32 v20, s2, v20
	v_add_u32_e32 v30, s2, v30
	v_add_u32_e32 v32, s2, v32
	v_subrev_u32_e32 v38, 33, v38
	v_add_u32_e32 v39, 32, v91
	v_ashrrev_i32_e32 v19, 31, v18
	v_ashrrev_i32_e32 v21, 31, v20
	v_ashrrev_i32_e32 v31, 31, v30
	v_ashrrev_i32_e32 v33, 31, v32
	v_cndmask_b32_e64 v38, v38, v39, s[16:17]
	v_lshlrev_b64 v[18:19], 10, v[18:19]
	v_lshlrev_b64 v[20:21], 10, v[20:21]
	v_lshlrev_b64 v[30:31], 10, v[30:31]
	v_lshlrev_b64 v[32:33], 10, v[32:33]
	v_add_u32_e32 v38, s2, v38
	v_lshl_add_u64 v[18:19], v[92:93], 0, v[18:19]
	v_lshl_add_u64 v[22:23], v[92:93], 0, v[20:21]
	v_lshl_add_u64 v[30:31], v[92:93], 0, v[30:31]
	v_lshl_add_u64 v[34:35], v[92:93], 0, v[32:33]
	v_mad_i64_i32 v[38:39], s[0:1], v38, s37, v[94:95]
	global_load_dwordx4 v[18:21], v[18:19], off
	s_nop 0
	global_load_dwordx4 v[22:25], v[22:23], off
	s_nop 0
	global_load_dwordx4 v[30:33], v[30:31], off
	s_nop 0
	global_load_dwordx4 v[34:37], v[34:35], off
	v_lshl_or_b32 v50, v50, 8, v106
	global_load_dwordx4 v[38:41], v[38:39], off
	s_movk_i32 s2, 0x600
	v_mad_u64_u32 v[96:97], s[0:1], v1, s2, v[50:51]
	v_readlane_b32 s0, v206, 24
	v_readlane_b32 s1, v206, 25
	v_lshlrev_b32_e32 v103, 2, v46
	v_mul_lo_u32 v50, v91, s2
	v_lshl_add_u64 v[98:99], v[46:47], 2, s[0:1]
	v_lshlrev_b32_e32 v46, 2, v48
	v_mad_u32_u24 v125, v87, s2, v153
	v_mad_u32_u24 v126, v87, s2, v154
	v_mad_u32_u24 v127, v87, s2, s2
	v_lshl_or_b32 v46, v1, 4, v46
	v_readlane_b32 s2, v206, 41
	s_waitcnt vmcnt(14)
	ds_write_b128 v96, v[52:55]
	s_waitcnt vmcnt(13)
	ds_write_b128 v96, v[56:59] offset:6144
	s_waitcnt vmcnt(12)
	ds_write_b128 v96, v[60:63] offset:12288
	s_waitcnt vmcnt(11)
	ds_write_b128 v96, v[64:67] offset:18432
	v_lshlrev_b32_e32 v51, 8, v51
	v_lshlrev_b32_e32 v52, 2, v72
	v_add_u32_e32 v128, s2, v46
	v_readlane_b32 s2, v206, 37
	v_or3_b32 v97, v50, v51, v52
	s_waitcnt vmcnt(10)
	v_lshlrev_b32_e32 v50, 16, v68
	v_and_b32_e32 v51, 0xffff0000, v68
	v_lshlrev_b32_e32 v52, 16, v69
	v_and_b32_e32 v53, 0xffff0000, v69
	v_lshlrev_b32_e32 v47, 2, v87
	v_add3_u32 v46, s2, v49, v48
	ds_write_b128 v97, v[50:53] offset:1024
	v_lshlrev_b32_e32 v50, 16, v70
	v_and_b32_e32 v51, 0xffff0000, v70
	v_lshlrev_b32_e32 v52, 16, v71
	v_and_b32_e32 v53, 0xffff0000, v71
	v_cmp_eq_u32_e64 s[0:1], 15, v87
	v_or_b32_e32 v105, 0x6000, v90
	v_or_b32_e32 v109, 0x6100, v90
	v_or_b32_e32 v110, 0x6200, v90
	v_or_b32_e32 v111, 0x6300, v90
	v_or_b32_e32 v112, 0x6400, v90
	v_or_b32_e32 v114, 0x6600, v90
	v_or_b32_e32 v115, 0x6700, v90
	v_or_b32_e32 v116, 0x6800, v90
	v_or_b32_e32 v117, 0x6900, v90
	v_or_b32_e32 v118, 0x6a00, v90
	v_or_b32_e32 v119, 0x6c00, v90
	v_or_b32_e32 v120, 0x6d00, v90
	v_or_b32_e32 v121, 0x6e00, v90
	v_or_b32_e32 v122, 0x6f00, v90
	v_or_b32_e32 v123, 0x7000, v90
	v_mul_u32_u24_e32 v124, 0x600, v87
	s_mov_b32 s7, 0
	v_sub_u32_e32 v129, 0, v87
	v_lshl_add_u32 v130, v46, 2, v155
	v_or_b32_e32 v131, 0x7200, v90
	v_lshlrev_b32_e32 v106, 2, v47
	v_readlane_b32 s3, v206, 7
	ds_write_b128 v97, v[50:53] offset:1040
	v_lshlrev_b32_e32 v102, 10, v1
	v_sub_u32_e32 v108, 0, v102
	v_cndmask_b32_e64 v254, v108, v102, s[16:17]
	v_ashrrev_i32_e32 v255, 31, v254
	v_lshl_add_u64 v[82:83], v[92:93], 0, v[254:255]
	v_add_u32_e32 v248, 0x1000, v102
	v_sub_u32_e32 v108, 0, v248
	v_cndmask_b32_e64 v254, v108, v248, s[16:17]
	v_ashrrev_i32_e32 v255, 31, v254
	v_lshl_add_u64 v[84:85], v[92:93], 0, v[254:255]
	v_add_u32_e32 v248, 0x2000, v102
	v_sub_u32_e32 v108, 0, v248
	v_cndmask_b32_e64 v254, v108, v248, s[16:17]
	v_ashrrev_i32_e32 v255, 31, v254
	v_lshl_add_u64 v[100:101], v[92:93], 0, v[254:255]
	v_add_u32_e32 v248, 0x3000, v102
	v_sub_u32_e32 v108, 0, v248
	v_cndmask_b32_e64 v254, v108, v248, s[16:17]
	v_ashrrev_i32_e32 v255, 31, v254
	v_lshl_add_u64 v[202:203], v[92:93], 0, v[254:255]
	v_mul_lo_u32 v248, v91, s37
	v_sub_u32_e32 v108, 0, v248
	v_cndmask_b32_e64 v254, v108, v248, s[16:17]
	v_ashrrev_i32_e32 v255, 31, v254
	v_lshl_add_u64 v[252:253], v[94:95], 0, v[254:255]
	s_waitcnt lgkmcnt(0)
	s_barrier

.Lrw_skip_pend_e:
	s_waitcnt lgkmcnt(12)
	v_pk_mul_f32 v[72:73], v[44:45], v[158:159]
	v_pk_mul_f32 v[74:75], v[42:43], v[160:161]
	v_pk_fma_f32 v[72:73], v[42:43], v[156:157], v[72:73]
	v_pk_mul_f32 v[76:77], v[44:45], v[162:163]
	v_add_f32_e32 v78, v72, v73
	v_pk_fma_f32 v[74:75], v[176:177], v[168:169], v[74:75] op_sel_hi:[0,1,1]
	v_pk_fma_f32 v[76:77], v[176:177], v[170:171], v[76:77] op_sel_hi:[0,1,1]
	v_add_f32_dpp v78, v78, v78 quad_perm:[1,0,3,2] row_mask:0xf bank_mask:0xf bound_ctrl:1
	ds_read_b128 v[210:213], v90 offset:4608
	ds_read_b128 v[214:217], v90 offset:4864
	v_add_f32_dpp v78, v78, v78 quad_perm:[2,3,0,1] row_mask:0xf bank_mask:0xf bound_ctrl:1
	ds_read_b128 v[222:225], v90 offset:5376
	ds_read_b32 v230, v103 offset:5888
	v_add_f32_dpp v78, v78, v78 row_half_mirror row_mask:0xf bank_mask:0xf bound_ctrl:1
	ds_read_b128 v[218:221], v90 offset:5120
	ds_read_b128 v[226:229], v90 offset:5632
	v_add_f32_dpp v78, v78, v78 row_mirror row_mask:0xf bank_mask:0xf bound_ctrl:1
	v_pk_fma_f32 v[44:45], v[166:167], v[78:79], v[76:77] op_sel_hi:[1,0,1]
	v_pk_fma_f32 v[42:43], v[164:165], v[78:79], v[74:75] op_sel_hi:[1,0,1]
	s_waitcnt lgkmcnt(12)
	v_pk_mul_f32 v[72:73], v[44:45], v[182:183]
	v_pk_mul_f32 v[80:81], v[44:45], v[174:175]
	v_pk_fma_f32 v[72:73], v[42:43], v[180:181], v[72:73]
	v_pk_fma_f32 v[80:81], v[42:43], v[172:173], v[80:81]
	v_add_f32_e32 v78, v72, v73
	v_add_f32_e32 v232, v80, v81
	v_pk_mul_f32 v[74:75], v[42:43], v[184:185]
	v_add_f32_dpp v78, v78, v78 quad_perm:[1,0,3,2] row_mask:0xf bank_mask:0xf bound_ctrl:1
	v_pk_mul_f32 v[76:77], v[44:45], v[186:187]
	v_pk_fma_f32 v[74:75], v[178:179], v[192:193], v[74:75] op_sel_hi:[0,1,1]
	v_add_f32_dpp v78, v78, v78 quad_perm:[2,3,0,1] row_mask:0xf bank_mask:0xf bound_ctrl:1
	v_pk_fma_f32 v[76:77], v[178:179], v[194:195], v[76:77] op_sel_hi:[0,1,1]
	ds_read_b128 v[156:159], v90 offset:6144
	v_add_f32_dpp v78, v78, v78 row_half_mirror row_mask:0xf bank_mask:0xf bound_ctrl:1
	ds_read_b128 v[160:163], v90 offset:6400
	ds_read_b128 v[168:171], v90 offset:6912
	v_add_f32_dpp v78, v78, v78 row_mirror row_mask:0xf bank_mask:0xf bound_ctrl:1
	v_pk_fma_f32 v[44:45], v[190:191], v[78:79], v[76:77] op_sel_hi:[1,0,1]
	v_pk_fma_f32 v[42:43], v[188:189], v[78:79], v[74:75] op_sel_hi:[1,0,1]
	ds_read_b32 v176, v103 offset:7424
	ds_read_b128 v[164:167], v90 offset:6656
	ds_read_b128 v[172:175], v90 offset:7168
	s_waitcnt lgkmcnt(12)
	v_pk_mul_f32 v[72:73], v[44:45], v[54:55]
	v_pk_mul_f32 v[80:81], v[44:45], v[198:199]
	v_pk_fma_f32 v[72:73], v[42:43], v[52:53], v[72:73]
	v_pk_fma_f32 v[80:81], v[42:43], v[196:197], v[80:81]
	v_add_f32_e32 v78, v72, v73
	v_add_f32_e32 v233, v80, v81
	v_pk_mul_f32 v[74:75], v[42:43], v[56:57]
	v_add_f32_dpp v78, v78, v78 quad_perm:[1,0,3,2] row_mask:0xf bank_mask:0xf bound_ctrl:1
	v_pk_mul_f32 v[76:77], v[44:45], v[58:59]
	v_pk_fma_f32 v[74:75], v[200:201], v[64:65], v[74:75] op_sel_hi:[0,1,1]
	v_add_f32_dpp v78, v78, v78 quad_perm:[2,3,0,1] row_mask:0xf bank_mask:0xf bound_ctrl:1
	v_pk_fma_f32 v[76:77], v[200:201], v[66:67], v[76:77] op_sel_hi:[0,1,1]
	ds_read_b128 v[180:183], v90 offset:7680
	v_add_f32_dpp v78, v78, v78 row_half_mirror row_mask:0xf bank_mask:0xf bound_ctrl:1
	ds_read_b128 v[184:187], v90 offset:7936
	ds_read_b128 v[192:195], v90 offset:8448
	v_add_f32_dpp v78, v78, v78 row_mirror row_mask:0xf bank_mask:0xf bound_ctrl:1
	v_pk_fma_f32 v[44:45], v[62:63], v[78:79], v[76:77] op_sel_hi:[1,0,1]
	v_pk_fma_f32 v[42:43], v[60:61], v[78:79], v[74:75] op_sel_hi:[1,0,1]
	ds_read_b32 v178, v103 offset:8960
	ds_read_b128 v[188:191], v90 offset:8192
	ds_read_b128 v[196:199], v90 offset:8704
	s_waitcnt lgkmcnt(12)
	v_pk_mul_f32 v[72:73], v[44:45], v[212:213]
	v_pk_mul_f32 v[80:81], v[44:45], v[70:71]
	v_pk_fma_f32 v[72:73], v[42:43], v[210:211], v[72:73]
	v_pk_fma_f32 v[80:81], v[42:43], v[68:69], v[80:81]
	v_add_f32_e32 v78, v72, v73
	v_add_f32_e32 v234, v80, v81
	v_pk_mul_f32 v[74:75], v[42:43], v[214:215]
	v_add_f32_dpp v78, v78, v78 quad_perm:[1,0,3,2] row_mask:0xf bank_mask:0xf bound_ctrl:1
	v_pk_mul_f32 v[76:77], v[44:45], v[216:217]
	v_pk_fma_f32 v[74:75], v[230:231], v[222:223], v[74:75] op_sel_hi:[0,1,1]
	v_add_f32_dpp v78, v78, v78 quad_perm:[2,3,0,1] row_mask:0xf bank_mask:0xf bound_ctrl:1
	v_pk_fma_f32 v[76:77], v[230:231], v[224:225], v[76:77] op_sel_hi:[0,1,1]
	ds_read_b128 v[52:55], v90 offset:9216
	v_add_f32_dpp v78, v78, v78 row_half_mirror row_mask:0xf bank_mask:0xf bound_ctrl:1
	ds_read_b128 v[56:59], v90 offset:9472
	ds_read_b128 v[64:67], v90 offset:9984
	v_add_f32_dpp v78, v78, v78 row_mirror row_mask:0xf bank_mask:0xf bound_ctrl:1
	v_pk_fma_f32 v[44:45], v[220:221], v[78:79], v[76:77] op_sel_hi:[1,0,1]
	v_pk_fma_f32 v[42:43], v[218:219], v[78:79], v[74:75] op_sel_hi:[1,0,1]
	ds_read_b32 v200, v103 offset:10496
	ds_read_b128 v[60:63], v90 offset:9728
	ds_read_b128 v[68:71], v90 offset:10240
	s_waitcnt lgkmcnt(12)
	v_pk_mul_f32 v[72:73], v[44:45], v[158:159]
	v_pk_mul_f32 v[80:81], v[44:45], v[228:229]
	v_pk_fma_f32 v[72:73], v[42:43], v[156:157], v[72:73]
	v_pk_fma_f32 v[80:81], v[42:43], v[226:227], v[80:81]
	v_add_f32_e32 v78, v72, v73
	v_add_f32_e32 v235, v80, v81
	v_pk_mul_f32 v[74:75], v[42:43], v[160:161]
	v_add_f32_dpp v78, v78, v78 quad_perm:[1,0,3,2] row_mask:0xf bank_mask:0xf bound_ctrl:1
	v_pk_mul_f32 v[76:77], v[44:45], v[162:163]
	v_pk_fma_f32 v[74:75], v[176:177], v[168:169], v[74:75] op_sel_hi:[0,1,1]
	v_add_f32_dpp v78, v78, v78 quad_perm:[2,3,0,1] row_mask:0xf bank_mask:0xf bound_ctrl:1
	v_pk_fma_f32 v[76:77], v[176:177], v[170:171], v[76:77] op_sel_hi:[0,1,1]
	ds_read_b128 v[210:213], v90 offset:10752
	v_add_f32_dpp v78, v78, v78 row_half_mirror row_mask:0xf bank_mask:0xf bound_ctrl:1
	ds_read_b128 v[214:217], v90 offset:11008
	ds_read_b128 v[222:225], v90 offset:11520
	v_add_f32_dpp v78, v78, v78 row_mirror row_mask:0xf bank_mask:0xf bound_ctrl:1
	v_pk_fma_f32 v[44:45], v[166:167], v[78:79], v[76:77] op_sel_hi:[1,0,1]
	v_pk_fma_f32 v[42:43], v[164:165], v[78:79], v[74:75] op_sel_hi:[1,0,1]
	ds_read_b32 v230, v103 offset:12032
	ds_read_b128 v[218:221], v90 offset:11264
	ds_read_b128 v[226:229], v90 offset:11776
	s_waitcnt lgkmcnt(12)
	v_pk_mul_f32 v[72:73], v[44:45], v[182:183]
	v_pk_mul_f32 v[80:81], v[44:45], v[174:175]
	v_pk_fma_f32 v[72:73], v[42:43], v[180:181], v[72:73]
	v_pk_fma_f32 v[80:81], v[42:43], v[172:173], v[80:81]
	v_add_f32_e32 v78, v72, v73
	v_add_f32_e32 v236, v80, v81
	v_pk_mul_f32 v[74:75], v[42:43], v[184:185]
	v_add_f32_dpp v78, v78, v78 quad_perm:[1,0,3,2] row_mask:0xf bank_mask:0xf bound_ctrl:1
	v_pk_mul_f32 v[76:77], v[44:45], v[186:187]
	v_pk_fma_f32 v[74:75], v[178:179], v[192:193], v[74:75] op_sel_hi:[0,1,1]
	v_add_f32_dpp v78, v78, v78 quad_perm:[2,3,0,1] row_mask:0xf bank_mask:0xf bound_ctrl:1
	v_pk_fma_f32 v[76:77], v[178:179], v[194:195], v[76:77] op_sel_hi:[0,1,1]
	ds_read_b128 v[156:159], v90 offset:12288
	v_add_f32_dpp v78, v78, v78 row_half_mirror row_mask:0xf bank_mask:0xf bound_ctrl:1
	ds_read_b128 v[160:163], v90 offset:12544
	ds_read_b128 v[168:171], v90 offset:13056
	v_add_f32_dpp v78, v78, v78 row_mirror row_mask:0xf bank_mask:0xf bound_ctrl:1
	v_pk_fma_f32 v[44:45], v[190:191], v[78:79], v[76:77] op_sel_hi:[1,0,1]
	v_pk_fma_f32 v[42:43], v[188:189], v[78:79], v[74:75] op_sel_hi:[1,0,1]
	ds_read_b32 v176, v103 offset:13568
	ds_read_b128 v[164:167], v90 offset:12800
	ds_read_b128 v[172:175], v90 offset:13312
	s_waitcnt lgkmcnt(12)
	v_pk_mul_f32 v[72:73], v[44:45], v[54:55]
	v_pk_mul_f32 v[80:81], v[44:45], v[198:199]
	v_pk_fma_f32 v[72:73], v[42:43], v[52:53], v[72:73]
	v_pk_fma_f32 v[80:81], v[42:43], v[196:197], v[80:81]
	v_add_f32_e32 v78, v72, v73
	v_add_f32_e32 v237, v80, v81
	v_pk_mul_f32 v[74:75], v[42:43], v[56:57]
	v_add_f32_dpp v78, v78, v78 quad_perm:[1,0,3,2] row_mask:0xf bank_mask:0xf bound_ctrl:1
	v_pk_mul_f32 v[76:77], v[44:45], v[58:59]
	v_pk_fma_f32 v[74:75], v[200:201], v[64:65], v[74:75] op_sel_hi:[0,1,1]
	v_add_f32_dpp v78, v78, v78 quad_perm:[2,3,0,1] row_mask:0xf bank_mask:0xf bound_ctrl:1
	v_pk_fma_f32 v[76:77], v[200:201], v[66:67], v[76:77] op_sel_hi:[0,1,1]
	ds_read_b128 v[180:183], v90 offset:13824
	v_add_f32_dpp v78, v78, v78 row_half_mirror row_mask:0xf bank_mask:0xf bound_ctrl:1
	ds_read_b128 v[184:187], v90 offset:14080
	ds_read_b128 v[192:195], v90 offset:14592
	v_add_f32_dpp v78, v78, v78 row_mirror row_mask:0xf bank_mask:0xf bound_ctrl:1
	v_pk_fma_f32 v[44:45], v[62:63], v[78:79], v[76:77] op_sel_hi:[1,0,1]
	v_pk_fma_f32 v[42:43], v[60:61], v[78:79], v[74:75] op_sel_hi:[1,0,1]
	ds_read_b32 v178, v103 offset:15104
	ds_read_b128 v[188:191], v90 offset:14336
	ds_read_b128 v[196:199], v90 offset:14848
	s_waitcnt lgkmcnt(12)
	v_pk_mul_f32 v[72:73], v[44:45], v[212:213]
	v_pk_mul_f32 v[80:81], v[44:45], v[70:71]
	v_pk_fma_f32 v[72:73], v[42:43], v[210:211], v[72:73]
	v_pk_fma_f32 v[80:81], v[42:43], v[68:69], v[80:81]
	v_add_f32_e32 v78, v72, v73
	v_add_f32_e32 v238, v80, v81
	v_pk_mul_f32 v[74:75], v[42:43], v[214:215]
	v_add_f32_dpp v78, v78, v78 quad_perm:[1,0,3,2] row_mask:0xf bank_mask:0xf bound_ctrl:1
	v_pk_mul_f32 v[76:77], v[44:45], v[216:217]
	v_pk_fma_f32 v[74:75], v[230:231], v[222:223], v[74:75] op_sel_hi:[0,1,1]
	v_add_f32_dpp v78, v78, v78 quad_perm:[2,3,0,1] row_mask:0xf bank_mask:0xf bound_ctrl:1
	v_pk_fma_f32 v[76:77], v[230:231], v[224:225], v[76:77] op_sel_hi:[0,1,1]
	ds_read_b128 v[52:55], v90 offset:15360
	v_add_f32_dpp v78, v78, v78 row_half_mirror row_mask:0xf bank_mask:0xf bound_ctrl:1
	ds_read_b128 v[56:59], v90 offset:15616
	ds_read_b128 v[64:67], v90 offset:16128
	v_add_f32_dpp v78, v78, v78 row_mirror row_mask:0xf bank_mask:0xf bound_ctrl:1
	v_pk_fma_f32 v[44:45], v[220:221], v[78:79], v[76:77] op_sel_hi:[1,0,1]
	v_pk_fma_f32 v[42:43], v[218:219], v[78:79], v[74:75] op_sel_hi:[1,0,1]
	ds_read_b32 v200, v103 offset:16640
	ds_read_b128 v[60:63], v90 offset:15872
	ds_read_b128 v[68:71], v90 offset:16384
	s_waitcnt lgkmcnt(12)
	v_pk_mul_f32 v[72:73], v[44:45], v[158:159]
	v_pk_mul_f32 v[80:81], v[44:45], v[228:229]
	v_pk_fma_f32 v[72:73], v[42:43], v[156:157], v[72:73]
	v_pk_fma_f32 v[80:81], v[42:43], v[226:227], v[80:81]
	v_add_f32_e32 v78, v72, v73
	v_add_f32_e32 v239, v80, v81
	v_pk_mul_f32 v[74:75], v[42:43], v[160:161]
	v_add_f32_dpp v78, v78, v78 quad_perm:[1,0,3,2] row_mask:0xf bank_mask:0xf bound_ctrl:1
	v_pk_mul_f32 v[76:77], v[44:45], v[162:163]
	v_pk_fma_f32 v[74:75], v[176:177], v[168:169], v[74:75] op_sel_hi:[0,1,1]
	v_add_f32_dpp v78, v78, v78 quad_perm:[2,3,0,1] row_mask:0xf bank_mask:0xf bound_ctrl:1
	v_pk_fma_f32 v[76:77], v[176:177], v[170:171], v[76:77] op_sel_hi:[0,1,1]
	ds_read_b128 v[210:213], v90 offset:16896
	v_add_f32_dpp v78, v78, v78 row_half_mirror row_mask:0xf bank_mask:0xf bound_ctrl:1
	ds_read_b128 v[214:217], v90 offset:17152
	ds_read_b128 v[222:225], v90 offset:17664
	v_add_f32_dpp v78, v78, v78 row_mirror row_mask:0xf bank_mask:0xf bound_ctrl:1
	v_pk_fma_f32 v[44:45], v[166:167], v[78:79], v[76:77] op_sel_hi:[1,0,1]
	v_pk_fma_f32 v[42:43], v[164:165], v[78:79], v[74:75] op_sel_hi:[1,0,1]
	ds_read_b32 v230, v103 offset:18176
	ds_read_b128 v[218:221], v90 offset:17408
	ds_read_b128 v[226:229], v90 offset:17920
	s_waitcnt lgkmcnt(12)
	v_pk_mul_f32 v[72:73], v[44:45], v[182:183]
	v_pk_mul_f32 v[80:81], v[44:45], v[174:175]
	v_pk_fma_f32 v[72:73], v[42:43], v[180:181], v[72:73]
	v_pk_fma_f32 v[80:81], v[42:43], v[172:173], v[80:81]
	v_add_f32_e32 v78, v72, v73
	v_add_f32_e32 v240, v80, v81
	v_pk_mul_f32 v[74:75], v[42:43], v[184:185]
	v_add_f32_dpp v78, v78, v78 quad_perm:[1,0,3,2] row_mask:0xf bank_mask:0xf bound_ctrl:1
	v_pk_mul_f32 v[76:77], v[44:45], v[186:187]
	v_pk_fma_f32 v[74:75], v[178:179], v[192:193], v[74:75] op_sel_hi:[0,1,1]
	v_add_f32_dpp v78, v78, v78 quad_perm:[2,3,0,1] row_mask:0xf bank_mask:0xf bound_ctrl:1
	v_pk_fma_f32 v[76:77], v[178:179], v[194:195], v[76:77] op_sel_hi:[0,1,1]
	ds_read_b128 v[156:159], v90 offset:18432
	v_add_f32_dpp v78, v78, v78 row_half_mirror row_mask:0xf bank_mask:0xf bound_ctrl:1
	ds_read_b128 v[160:163], v90 offset:18688
	ds_read_b128 v[168:171], v90 offset:19200
	v_add_f32_dpp v78, v78, v78 row_mirror row_mask:0xf bank_mask:0xf bound_ctrl:1
	v_pk_fma_f32 v[44:45], v[190:191], v[78:79], v[76:77] op_sel_hi:[1,0,1]
	v_pk_fma_f32 v[42:43], v[188:189], v[78:79], v[74:75] op_sel_hi:[1,0,1]
	ds_read_b32 v176, v103 offset:19712
	ds_read_b128 v[164:167], v90 offset:18944
	ds_read_b128 v[172:175], v90 offset:19456
	s_waitcnt lgkmcnt(12)
	v_pk_mul_f32 v[72:73], v[44:45], v[54:55]
	v_pk_mul_f32 v[80:81], v[44:45], v[198:199]
	v_pk_fma_f32 v[72:73], v[42:43], v[52:53], v[72:73]
	v_pk_fma_f32 v[80:81], v[42:43], v[196:197], v[80:81]
	v_add_f32_e32 v78, v72, v73
	v_add_f32_e32 v241, v80, v81
	v_pk_mul_f32 v[74:75], v[42:43], v[56:57]
	v_add_f32_dpp v78, v78, v78 quad_perm:[1,0,3,2] row_mask:0xf bank_mask:0xf bound_ctrl:1
	v_pk_mul_f32 v[76:77], v[44:45], v[58:59]
	v_pk_fma_f32 v[74:75], v[200:201], v[64:65], v[74:75] op_sel_hi:[0,1,1]
	v_add_f32_dpp v78, v78, v78 quad_perm:[2,3,0,1] row_mask:0xf bank_mask:0xf bound_ctrl:1
	v_pk_fma_f32 v[76:77], v[200:201], v[66:67], v[76:77] op_sel_hi:[0,1,1]
	ds_read_b128 v[180:183], v90 offset:19968
	v_add_f32_dpp v78, v78, v78 row_half_mirror row_mask:0xf bank_mask:0xf bound_ctrl:1
	ds_read_b128 v[184:187], v90 offset:20224
	ds_read_b128 v[192:195], v90 offset:20736
	v_add_f32_dpp v78, v78, v78 row_mirror row_mask:0xf bank_mask:0xf bound_ctrl:1
	v_pk_fma_f32 v[44:45], v[62:63], v[78:79], v[76:77] op_sel_hi:[1,0,1]
	v_pk_fma_f32 v[42:43], v[60:61], v[78:79], v[74:75] op_sel_hi:[1,0,1]
	ds_read_b32 v178, v103 offset:21248
	ds_read_b128 v[188:191], v90 offset:20480
	ds_read_b128 v[196:199], v90 offset:20992
	s_waitcnt lgkmcnt(12)
	v_pk_mul_f32 v[72:73], v[44:45], v[212:213]
	v_pk_mul_f32 v[80:81], v[44:45], v[70:71]
	v_pk_fma_f32 v[72:73], v[42:43], v[210:211], v[72:73]
	v_pk_fma_f32 v[80:81], v[42:43], v[68:69], v[80:81]
	v_add_f32_e32 v78, v72, v73
	v_add_f32_e32 v242, v80, v81
	v_pk_mul_f32 v[74:75], v[42:43], v[214:215]
	v_add_f32_dpp v78, v78, v78 quad_perm:[1,0,3,2] row_mask:0xf bank_mask:0xf bound_ctrl:1
	v_pk_mul_f32 v[76:77], v[44:45], v[216:217]
	v_pk_fma_f32 v[74:75], v[230:231], v[222:223], v[74:75] op_sel_hi:[0,1,1]
	v_add_f32_dpp v78, v78, v78 quad_perm:[2,3,0,1] row_mask:0xf bank_mask:0xf bound_ctrl:1
	v_pk_fma_f32 v[76:77], v[230:231], v[224:225], v[76:77] op_sel_hi:[0,1,1]
	ds_read_b128 v[52:55], v90 offset:21504
	v_add_f32_dpp v78, v78, v78 row_half_mirror row_mask:0xf bank_mask:0xf bound_ctrl:1
	ds_read_b128 v[56:59], v90 offset:21760
	ds_read_b128 v[64:67], v90 offset:22272
	v_add_f32_dpp v78, v78, v78 row_mirror row_mask:0xf bank_mask:0xf bound_ctrl:1
	v_pk_fma_f32 v[44:45], v[220:221], v[78:79], v[76:77] op_sel_hi:[1,0,1]
	v_pk_fma_f32 v[42:43], v[218:219], v[78:79], v[74:75] op_sel_hi:[1,0,1]
	ds_read_b32 v200, v103 offset:22784
	ds_read_b128 v[60:63], v90 offset:22016
	ds_read_b128 v[68:71], v90 offset:22528
	s_waitcnt lgkmcnt(12)
	v_pk_mul_f32 v[72:73], v[44:45], v[158:159]
	v_pk_mul_f32 v[80:81], v[44:45], v[228:229]
	v_pk_fma_f32 v[72:73], v[42:43], v[156:157], v[72:73]
	v_pk_fma_f32 v[80:81], v[42:43], v[226:227], v[80:81]
	v_add_f32_e32 v78, v72, v73
	v_add_f32_e32 v243, v80, v81
	v_pk_mul_f32 v[74:75], v[42:43], v[160:161]
	v_add_f32_dpp v78, v78, v78 quad_perm:[1,0,3,2] row_mask:0xf bank_mask:0xf bound_ctrl:1
	v_pk_mul_f32 v[76:77], v[44:45], v[162:163]
	v_pk_fma_f32 v[74:75], v[176:177], v[168:169], v[74:75] op_sel_hi:[0,1,1]
	v_add_f32_dpp v78, v78, v78 quad_perm:[2,3,0,1] row_mask:0xf bank_mask:0xf bound_ctrl:1
	v_pk_fma_f32 v[76:77], v[176:177], v[170:171], v[76:77] op_sel_hi:[0,1,1]
	ds_read_b128 v[210:213], v90 offset:23040
	v_add_f32_dpp v78, v78, v78 row_half_mirror row_mask:0xf bank_mask:0xf bound_ctrl:1
	ds_read_b128 v[214:217], v90 offset:23296
	ds_read_b128 v[222:225], v90 offset:23808
	v_add_f32_dpp v78, v78, v78 row_mirror row_mask:0xf bank_mask:0xf bound_ctrl:1
	v_pk_fma_f32 v[44:45], v[166:167], v[78:79], v[76:77] op_sel_hi:[1,0,1]
	v_pk_fma_f32 v[42:43], v[164:165], v[78:79], v[74:75] op_sel_hi:[1,0,1]
	ds_read_b32 v230, v103 offset:24320
	ds_read_b128 v[218:221], v90 offset:23552
	ds_read_b128 v[226:229], v90 offset:24064
	s_waitcnt lgkmcnt(12)
	v_pk_mul_f32 v[72:73], v[44:45], v[182:183]
	v_pk_mul_f32 v[80:81], v[44:45], v[174:175]
	v_pk_fma_f32 v[72:73], v[42:43], v[180:181], v[72:73]
	v_pk_fma_f32 v[80:81], v[42:43], v[172:173], v[80:81]
	v_add_f32_e32 v78, v72, v73
	v_add_f32_e32 v244, v80, v81
	v_pk_mul_f32 v[74:75], v[42:43], v[184:185]
	v_add_f32_dpp v78, v78, v78 quad_perm:[1,0,3,2] row_mask:0xf bank_mask:0xf bound_ctrl:1
	v_pk_mul_f32 v[76:77], v[44:45], v[186:187]
	v_pk_fma_f32 v[74:75], v[178:179], v[192:193], v[74:75] op_sel_hi:[0,1,1]
	v_add_f32_dpp v78, v78, v78 quad_perm:[2,3,0,1] row_mask:0xf bank_mask:0xf bound_ctrl:1
	v_pk_fma_f32 v[76:77], v[178:179], v[194:195], v[76:77] op_sel_hi:[0,1,1]
	s_nop 0
	v_add_f32_dpp v78, v78, v78 row_half_mirror row_mask:0xf bank_mask:0xf bound_ctrl:1
	s_nop 0
	s_nop 0
	v_add_f32_dpp v78, v78, v78 row_mirror row_mask:0xf bank_mask:0xf bound_ctrl:1
	v_pk_fma_f32 v[44:45], v[190:191], v[78:79], v[76:77] op_sel_hi:[1,0,1]
	v_pk_fma_f32 v[42:43], v[188:189], v[78:79], v[74:75] op_sel_hi:[1,0,1]
	s_waitcnt lgkmcnt(6)
	v_pk_mul_f32 v[72:73], v[44:45], v[54:55]
	v_pk_mul_f32 v[80:81], v[44:45], v[198:199]
	v_pk_fma_f32 v[72:73], v[42:43], v[52:53], v[72:73]
	v_pk_fma_f32 v[80:81], v[42:43], v[196:197], v[80:81]
	v_add_f32_e32 v78, v72, v73
	v_add_f32_e32 v245, v80, v81
	v_pk_mul_f32 v[74:75], v[42:43], v[56:57]
	v_add_f32_dpp v78, v78, v78 quad_perm:[1,0,3,2] row_mask:0xf bank_mask:0xf bound_ctrl:1
	v_pk_mul_f32 v[76:77], v[44:45], v[58:59]
	v_pk_fma_f32 v[74:75], v[200:201], v[64:65], v[74:75] op_sel_hi:[0,1,1]
	v_add_f32_dpp v78, v78, v78 quad_perm:[2,3,0,1] row_mask:0xf bank_mask:0xf bound_ctrl:1
	v_pk_fma_f32 v[76:77], v[200:201], v[66:67], v[76:77] op_sel_hi:[0,1,1]
	s_nop 0
	v_add_f32_dpp v78, v78, v78 row_half_mirror row_mask:0xf bank_mask:0xf bound_ctrl:1
	s_nop 0
	s_nop 0
	v_add_f32_dpp v78, v78, v78 row_mirror row_mask:0xf bank_mask:0xf bound_ctrl:1
	v_pk_fma_f32 v[44:45], v[62:63], v[78:79], v[76:77] op_sel_hi:[1,0,1]
	v_pk_fma_f32 v[42:43], v[60:61], v[78:79], v[74:75] op_sel_hi:[1,0,1]
	s_waitcnt lgkmcnt(0)
	v_pk_mul_f32 v[72:73], v[44:45], v[212:213]
	v_pk_mul_f32 v[80:81], v[44:45], v[70:71]
	v_pk_fma_f32 v[72:73], v[42:43], v[210:211], v[72:73]
	v_pk_fma_f32 v[80:81], v[42:43], v[68:69], v[80:81]
	v_add_f32_e32 v78, v72, v73
	v_add_f32_e32 v246, v80, v81
	v_pk_mul_f32 v[74:75], v[42:43], v[214:215]
	v_add_f32_dpp v78, v78, v78 quad_perm:[1,0,3,2] row_mask:0xf bank_mask:0xf bound_ctrl:1
	v_pk_mul_f32 v[76:77], v[44:45], v[216:217]
	v_pk_fma_f32 v[74:75], v[230:231], v[222:223], v[74:75] op_sel_hi:[0,1,1]
	v_add_f32_dpp v78, v78, v78 quad_perm:[2,3,0,1] row_mask:0xf bank_mask:0xf bound_ctrl:1
	v_pk_fma_f32 v[76:77], v[230:231], v[224:225], v[76:77] op_sel_hi:[0,1,1]
	s_nop 0
	v_add_f32_dpp v78, v78, v78 row_half_mirror row_mask:0xf bank_mask:0xf bound_ctrl:1
	s_nop 0
	s_nop 0
	v_add_f32_dpp v78, v78, v78 row_mirror row_mask:0xf bank_mask:0xf bound_ctrl:1
	v_pk_fma_f32 v[44:45], v[220:221], v[78:79], v[76:77] op_sel_hi:[1,0,1]
	v_pk_fma_f32 v[42:43], v[218:219], v[78:79], v[74:75] op_sel_hi:[1,0,1]
	v_pk_mul_f32 v[80:81], v[44:45], v[228:229]
	s_nop 0
	v_pk_fma_f32 v[80:81], v[42:43], v[226:227], v[80:81]
	s_nop 0
	v_add_f32_e32 v247, v80, v81
	s_waitcnt vmcnt(1)
	v_and_b32_e32 v49, 0xffff0000, v27
	s_add_i32 s2, s7, 3
	s_cmp_ge_u32 s2, s19
	v_lshlrev_b32_e32 v46, 16, v26
	v_and_b32_e32 v47, 0xffff0000, v26
	v_lshlrev_b32_e32 v48, 16, v27
	ds_write_b128 v96, v[2:5] offset:24576
	ds_write_b128 v96, v[6:9] offset:30720
	ds_write_b128 v96, v[10:13] offset:36864
	ds_write_b128 v96, v[14:17] offset:43008
	ds_write_b128 v97, v[46:49] offset:25600
	v_lshlrev_b32_e32 v46, 16, v28
	v_and_b32_e32 v47, 0xffff0000, v28
	v_lshlrev_b32_e32 v48, 16, v29
	v_and_b32_e32 v49, 0xffff0000, v29
	ds_write_b128 v97, v[46:49] offset:25616
	s_cbranch_scc1 .LBB0_1255
	s_lshl_b32 s2, s2, 4
	v_readlane_b32 s4, v206, 6
	s_sub_i32 s3, s18, s2
	s_add_i32 s3, s3, s4
	s_add_i32 s3, s3, -1
	s_add_i32 s2, s4, s2
	s_cmp_lg_u64 s[16:17], 0
	s_cselect_b32 s2, s2, s3
	s_ashr_i32 s5, s2, 31
	s_mov_b32 s4, s2
	s_lshl_b64 s[4:5], s[4:5], 10
	v_lshl_add_u64 v[2:3], v[82:83], 0, s[4:5]
	v_lshl_add_u64 v[6:7], v[84:85], 0, s[4:5]
	v_lshl_add_u64 v[10:11], v[100:101], 0, s[4:5]
	v_lshl_add_u64 v[14:15], v[202:203], 0, s[4:5]
	s_mul_hi_i32 s3, s2, s37
	s_mul_i32 s2, s2, s37
	v_lshl_add_u64 v[26:27], v[252:253], 0, s[2:3]
	global_load_dwordx4 v[2:5], v[2:3], off
	global_load_dwordx4 v[6:9], v[6:7], off
	global_load_dwordx4 v[10:13], v[10:11], off
	global_load_dwordx4 v[14:17], v[14:15], off
	v_readlane_b32 s4, v206, 6
	v_readlane_b32 s5, v206, 7
	global_load_dwordx4 v[26:29], v[26:27], off

.LBB0_1259:
	s_add_i32 s7, s7, 4
	s_cmp_ge_u32 s7, s19
	s_cbranch_scc1 .LBB0_1261
	s_lshl_b32 s7, s7, 4
	s_waitcnt vmcnt(2)
	v_readlane_b32 s4, v206, 6
	s_sub_i32 s13, s18, s7
	s_add_i32 s13, s13, s4
	s_add_i32 s13, s13, -1
	s_add_i32 s12, s4, s7
	s_cmp_lg_u64 s[16:17], 0
	s_cselect_b32 s12, s12, s13
	s_ashr_i32 s5, s12, 31
	s_mov_b32 s4, s12
	s_lshl_b64 s[4:5], s[4:5], 10
	v_lshl_add_u64 v[18:19], v[82:83], 0, s[4:5]
	v_lshl_add_u64 v[22:23], v[84:85], 0, s[4:5]
	v_lshl_add_u64 v[30:31], v[100:101], 0, s[4:5]
	v_lshl_add_u64 v[34:35], v[202:203], 0, s[4:5]
	s_mul_hi_i32 s13, s12, s37
	s_mul_i32 s12, s12, s37
	v_lshl_add_u64 v[38:39], v[252:253], 0, s[12:13]
	global_load_dwordx4 v[18:21], v[18:19], off
	global_load_dwordx4 v[22:25], v[22:23], off
	global_load_dwordx4 v[30:33], v[30:31], off
	global_load_dwordx4 v[34:37], v[34:35], off
	v_readlane_b32 s4, v206, 6
	v_readlane_b32 s5, v206, 7
	global_load_dwordx4 v[38:41], v[38:39], off
